# attention tile loop: exit mask test hoisted above the tile barrier, on top of the stacked loop-edge edits
# baseline (speedup 1.0000x reference)
; #define LAS __attribute__((address_space(3)))
; __device__ __forceinline__ void lds_barrier() { asm volatile("s_waitcnt lgkmcnt(0)" ::: "memory"); __builtin_amdgcn_s_barrier(); asm volatile("" ::: "memory"); }
; __device__ __forceinline__ void attn_phase(const Args& a, LAS unsigned char* lds, const bf16* Qn, const bf16* Kn, const bf16* Vt, bf16* O, float* stash, int tid, int lane, int wave) {
;     ...
;             for (int tp = 0; tp < NT; tp += 2) {
;     ...
;                 if (t + 1 < NT) { if (t + 2 < NT) asm volatile("s_waitcnt vmcnt(3)" ::: "memory"); else asm volatile("s_waitcnt vmcnt(0)" ::: "memory");
;                     LAS unsigned char* d = lds + ((t + 1) & 1) * AT_BUF; *(LAS u32x4*)(d + kofs) = kreg[hh ^ 1]; *(LAS u32x4*)(d + AT_KB + kofs) = vreg0[hh ^ 1]; *(LAS u32x4*)(d + AT_KB + 64 * 144 + kofs) = vreg1[hh ^ 1]; }
;                 lds_barrier();
.LBB0_124:
	v_lshl_add_u64 v[190:191], v[190:191], 0, s[26:27]
	v_lshl_add_u64 v[188:189], v[188:189], 0, s[26:27]
	v_lshl_add_u64 v[192:193], v[192:193], 0, s[18:19]
	s_and_b64 vcc, exec, s[20:21]
	s_waitcnt lgkmcnt(0)
	s_barrier
	s_cbranch_vccnz .LBB0_132
	s_mov_b32 s2, s41
	s_branch .LBB0_106
